# P0 row loop: the x row loads carry the nt (streaming) cache policy, on top of nt P1 epilogue stores
# speedup vs baseline: 1.0308x; 1.0165x over previous
; #define GAS __attribute__((address_space(1)))
; __device__ __forceinline__ void p0_prologue(const Args& a, LAS unsigned char* lds, int vcu, int G, int tid, int lane, int wave) {
;     ...
;     const GAS f32x4* gp = (const GAS f32x4*)n1g + lane;
;     f32x4 gv[4];
; #pragma unroll
;     for (int j = 0; j < 4; ++j) gv[j] = gp[64 * j];
;     f32x4 nv[4];
;     if (gw < T) { const GAS f32x4* xr0 = (const GAS f32x4*)(x + (size_t)gw * DM) + lane;
; #pragma unroll
;         for (int j = 0; j < 4; ++j) nv[j] = xr0[64 * j]; }
;     for (int m = gw; m < T; m += NGW) {
;         f32x4 v[4]; float s2 = 0.f;
; #pragma unroll
;         for (int j = 0; j < 4; ++j) { v[j] = nv[j]; s2 += (v[j].x * v[j].x + v[j].y * v[j].y) + (v[j].z * v[j].z + v[j].w * v[j].w); }
;         if (m + NGW < T) { const GAS f32x4* xr = (const GAS f32x4*)(x + (size_t)(m + NGW) * DM) + lane;
; #pragma unroll
;             for (int j = 0; j < 4; ++j) nv[j] = xr[64 * j]; }
.LBB0_54:
	s_or_b64 exec, exec, s[6:7]
	s_cmp_lt_i32 s62, 0x8000
	s_waitcnt lgkmcnt(0)
	s_barrier
	s_cbranch_scc0 .LBB0_61
	s_ashr_i32 s63, s62, 31
	s_lshl_b64 s[0:1], s[62:63], 12
	s_add_u32 s0, s36, s0
	v_lshlrev_b32_e32 v36, 4, v188
	s_addc_u32 s1, s37, s1
	global_load_dwordx4 v[2:5], v36, s[38:39]
	global_load_dwordx4 v[6:9], v36, s[38:39] offset:1024
	global_load_dwordx4 v[10:13], v36, s[38:39] offset:2048
	global_load_dwordx4 v[14:17], v36, s[38:39] offset:3072
	global_load_dwordx4 v[174:177], v36, s[0:1] nt
	global_load_dwordx4 v[170:173], v36, s[0:1] offset:1024 nt
	global_load_dwordx4 v[166:169], v36, s[0:1] offset:2048 nt
	global_load_dwordx4 v[162:165], v36, s[0:1] offset:3072 nt
	v_mbcnt_lo_u32_b32 v1, -1, 0
	v_mbcnt_hi_u32_b32 v18, -1, v1
	v_and_b32_e32 v1, 64, v18
	v_add_u32_e32 v19, 64, v1
	v_xor_b32_e32 v1, 1, v18
	v_cmp_lt_i32_e32 vcc, v1, v19
	v_xor_b32_e32 v20, 2, v18
	s_lshl_b64 s[18:19], s[62:63], 11
	v_cndmask_b32_e32 v1, v18, v1, vcc
	v_cmp_lt_i32_e32 vcc, v20, v19
	v_mov_b32_e32 v37, 0
	s_add_u32 s18, s26, s18
	v_cndmask_b32_e32 v20, v18, v20, vcc
	v_lshlrev_b32_e32 v189, 2, v20
	v_xor_b32_e32 v20, 4, v18
	v_cmp_lt_i32_e32 vcc, v20, v19
	v_mov_b32_e32 v35, v37
	s_addc_u32 s19, s27, s19
	v_cndmask_b32_e32 v20, v18, v20, vcc
	v_lshlrev_b32_e32 v190, 2, v20
	v_xor_b32_e32 v20, 8, v18
	v_cmp_lt_i32_e32 vcc, v20, v19
	v_lshl_add_u64 v[180:181], s[18:19], 0, v[34:35]
	s_add_i32 s18, s62, s34
	v_cndmask_b32_e32 v20, v18, v20, vcc
	v_lshlrev_b32_e32 v191, 2, v20
	v_xor_b32_e32 v20, 16, v18
	v_cmp_lt_i32_e32 vcc, v20, v19
	s_ashr_i32 s35, s34, 31
	s_ashr_i32 s19, s18, 31
	v_cndmask_b32_e32 v20, v18, v20, vcc
	v_lshlrev_b32_e32 v192, 2, v20
	v_xor_b32_e32 v20, 32, v18
	v_cmp_lt_i32_e32 vcc, v20, v19
	s_lshl_b64 s[40:41], s[34:35], 11
	s_lshl_b64 s[18:19], s[18:19], 12
	v_cndmask_b32_e32 v18, v18, v20, vcc
	v_lshlrev_b32_e32 v193, 2, v18
	v_add_u32_e32 v18, 0, v36
	s_add_u32 s18, s36, s18
	v_add_u32_e32 v142, 0x12000, v18
	v_lshlrev_b32_e32 v18, 2, v188
	v_mov_b32_e32 v19, v37
	s_addc_u32 s19, s37, s19
	v_lshl_add_u64 v[178:179], s[50:51], 0, v[18:19]
	ds_read_b128 v[18:21], v142
	ds_read_b128 v[22:25], v142 offset:1024
	ds_read_b128 v[26:29], v142 offset:2048
	ds_read_b128 v[30:33], v142 offset:3072
	v_lshl_add_u64 v[182:183], s[18:19], 0, v[36:37]
	ds_read_b128 v[34:37], v142 offset:4096
	ds_read_b128 v[38:41], v142 offset:5120
	ds_read_b128 v[42:45], v142 offset:6144
	ds_read_b128 v[46:49], v142 offset:7168
	ds_read_b128 v[50:53], v142 offset:8192
	ds_read_b128 v[54:57], v142 offset:9216
	ds_read_b128 v[58:61], v142 offset:10240
	ds_read_b128 v[62:65], v142 offset:11264
	ds_read_b128 v[66:69], v142 offset:12288
	ds_read_b128 v[70:73], v142 offset:13312
	ds_read_b128 v[74:77], v142 offset:14336
	ds_read_b128 v[78:81], v142 offset:15360
	ds_read_b128 v[82:85], v142 offset:16384
	ds_read_b128 v[86:89], v142 offset:17408
	ds_read_b128 v[90:93], v142 offset:18432
	ds_read_b128 v[94:97], v142 offset:19456
	ds_read_b128 v[98:101], v142 offset:20480
	ds_read_b128 v[102:105], v142 offset:21504
	ds_read_b128 v[106:109], v142 offset:22528
	ds_read_b128 v[110:113], v142 offset:23552
	ds_read_b128 v[114:117], v142 offset:24576
	ds_read_b128 v[118:121], v142 offset:25600
	ds_read_b128 v[122:125], v142 offset:26624
	ds_read_b128 v[126:129], v142 offset:27648
	ds_read_b128 v[130:133], v142 offset:28672
	ds_read_b128 v[134:137], v142 offset:29696
	ds_read_b128 v[138:141], v142 offset:30720
	ds_read_b128 v[142:145], v142 offset:31744
	s_mov_b32 s39, 0
	v_lshlrev_b32_e32 v1, 2, v1
	v_cmp_gt_u32_e64 s[0:1], 8, v188
	v_cmp_eq_u32_e64 s[16:17], 7, v188
	v_cmp_eq_u32_e64 s[4:5], 6, v188
	v_cmp_eq_u32_e64 s[6:7], 5, v188
	v_cmp_eq_u32_e64 s[8:9], 4, v188
	v_cmp_eq_u32_e64 s[10:11], 3, v188
	v_cmp_eq_u32_e64 s[12:13], 2, v188
	v_cmp_eq_u32_e64 s[14:15], 1, v188
	s_lshl_b64 s[46:47], s[34:35], 12
	v_mov_b32_e32 v194, 0x358637bd
	s_mov_b32 s33, 0xf800000
	v_mov_b32_e32 v195, 0x260
	s_mov_b32 s35, 0xbfb8aa3b
	s_mov_b32 s54, 0xb2a5705f
	s_mov_b32 s55, 0x42ce8ed0
	s_mov_b32 s56, 0xc2b17218
	s_mov_b32 s57, 0x7f800000
	s_mov_b32 s58, 0x3f2aaaab
	v_mov_b32_e32 v196, 0x3ecc95a3
	s_mov_b32 s59, 0x3f317218
	s_mov_b32 s63, 0x33800000
	v_mov_b32_e32 v197, 0x7f800000
	v_mov_b32_e32 v184, 0x3f317218
	s_waitcnt vmcnt(3)
	v_mov_b64_e32 v[158:159], v[174:175]
	s_waitcnt vmcnt(2)
	v_mov_b64_e32 v[154:155], v[170:171]
	s_waitcnt vmcnt(1)
	v_mov_b64_e32 v[150:151], v[166:167]
	s_waitcnt vmcnt(0)
	v_mov_b64_e32 v[146:147], v[162:163]
	v_mov_b64_e32 v[148:149], v[164:165]
	v_mov_b64_e32 v[152:153], v[168:169]
	v_mov_b64_e32 v[156:157], v[172:173]
	v_mov_b64_e32 v[160:161], v[176:177]
	s_branch .LBB0_57

; #define GAS __attribute__((address_space(1)))
; __device__ __forceinline__ void p0_prologue(const Args& a, LAS unsigned char* lds, int vcu, int G, int tid, int lane, int wave) {
;     ...
;     for (int m = gw; m < T; m += NGW) {
;         f32x4 v[4]; float s2 = 0.f;
; #pragma unroll
;         for (int j = 0; j < 4; ++j) { v[j] = nv[j]; s2 += (v[j].x * v[j].x + v[j].y * v[j].y) + (v[j].z * v[j].z + v[j].w * v[j].w); }
;         if (m + NGW < T) { const GAS f32x4* xr = (const GAS f32x4*)(x + (size_t)(m + NGW) * DM) + lane;
; #pragma unroll
;             for (int j = 0; j < 4; ++j) nv[j] = xr[64 * j]; }
.LBB0_57:
	s_add_i32 s64, s62, s34
	s_cmpk_gt_i32 s64, 0x7fff
	s_cselect_b64 s[50:51], -1, 0
	s_and_b64 vcc, exec, s[50:51]
	s_cbranch_vccnz .LBB0_59
	global_load_dwordx4 v[158:161], v[182:183], off nt
	global_load_dwordx4 v[154:157], v[182:183], off offset:1024 nt
	global_load_dwordx4 v[150:153], v[182:183], off offset:2048 nt
	global_load_dwordx4 v[146:149], v[182:183], off offset:3072 nt
